# phase-0 transposed weight stores write-through (sc1)
# speedup vs baseline: 1.0103x; 1.0103x over previous
.LBB0_48:
	s_or_b64 exec, exec, s[6:7]
	v_ashrrev_i32_e32 v51, 31, v50
	v_lshlrev_b64 v[50:51], 12, v[50:51]
	s_lshl_b32 s6, s3, 6
	v_lshl_add_u64 v[50:51], s[82:83], 0, v[50:51]
	s_ashr_i32 s7, s6, 31
	v_lshl_add_u64 v[50:51], s[6:7], 1, v[50:51]
	v_mov_b32_e32 v39, v129
	v_lshl_add_u64 v[84:85], v[50:51], 0, v[38:39]
	s_waitcnt lgkmcnt(14)
	v_cvt_pk_bf16_f32 v50, v43, v52
	s_waitcnt lgkmcnt(12)
	v_cvt_pk_bf16_f32 v51, v53, v60
	s_waitcnt lgkmcnt(10)
	v_cvt_pk_bf16_f32 v52, v61, v68
	s_waitcnt lgkmcnt(8)
	v_cvt_pk_bf16_f32 v53, v69, v75
	s_add_i32 s29, s29, s33
	v_add_u32_e32 v35, s34, v35
	s_andn2_b64 vcc, exec, s[4:5]
	s_mov_b32 s64, s63
	v_cvt_pk_bf16_f32 v80, v57, v64
	v_cvt_pk_bf16_f32 v81, v65, v71
	v_cvt_pk_bf16_f32 v82, v72, v76
	v_cvt_pk_bf16_f32 v83, v77, v79
	global_store_dwordx4 v[84:85], v[80:83], off sc1
	v_cvt_pk_bf16_f32 v64, v49, v58
	v_cvt_pk_bf16_f32 v65, v59, v66
	v_cvt_pk_bf16_f32 v66, v67, v73
	v_cvt_pk_bf16_f32 v67, v74, v78
	global_store_dwordx4 v[84:85], v[64:67], off offset:16 sc1
	global_store_dwordx4 v[84:85], v[50:53], off offset:32 sc1
	s_waitcnt lgkmcnt(6)
	s_nop 0
	v_cvt_pk_bf16_f32 v50, v41, v45
	s_waitcnt lgkmcnt(4)
	v_cvt_pk_bf16_f32 v51, v47, v54
	s_waitcnt lgkmcnt(2)
	v_cvt_pk_bf16_f32 v52, v55, v62
	s_waitcnt lgkmcnt(0)
	v_cvt_pk_bf16_f32 v53, v63, v70
	global_store_dwordx4 v[84:85], v[50:53], off offset:48 sc1
	s_barrier
	s_cbranch_vccz .LBB0_75
